# v9: ACT (SwiGLU output) stored in LDS-image order so FFN-out A tiles stage as contiguous 1KB pieces; plus v1 batched residual loads
# baseline (speedup 1.0000x reference)
; template <class Epi>
; __device__ __forceinline__ void gemm_phase(LAS unsigned char* lds, const Gemm g, const StaticOrder& S, const Epi& E) {
;     ...
;     unsigned voffA[2], voffB[2];
; #pragma unroll
;     for (int i = 0; i < 2; ++i) { int R, C; stage_rc(tid * 16 + i * 8192, R, C); const int Rb = Epi::PERM ? ((R & ~31) + perm32(R & 31)) : R;
;         voffA[i] = (unsigned)(R * g.lda + C) * 2u; voffB[i] = (unsigned)(Rb * g.ldb + C) * 2u; }
;     const size_t kstep = (size_t)(BK * 2);
;     const size_t hstepA = (size_t)HALF * g.lda * 2, hstepB = (size_t)HALF * g.ldb * 2;
; __global__ void __launch_bounds__(NTHREADS, 2) fwd_megakernel(Params p) {
;     ...
;                 if (k == 12) g = pg8::Gemm{(const bf16_t*)(ws + WS_U), (const bf16_t*)(ws + WS_WOUTT) + (size_t)l * DM * DM, DM, DM, T, DM, DM};
;                 else g = pg8::Gemm{(const bf16_t*)(ws + WS_R1), (const bf16_t*)(ws + WS_W2T) + (size_t)(l * 2 + (k == 2 ? 0 : 1)) * DM * DFF, DFF, DFF, T, DM, DFF};
;                 pg8::StaticOrder S; S.init(g.M, g.N, G, blockIdx.x);
;                 const int gi = k == 2 ? 2 : (k == 12 ? 5 : 8);
;                 for (int rep = 0; rep < NREP(3); ++rep) {
;                     const bool fuse = FUSE_NORM && G == 256 && !(k == 15 && l == DEPTH - 1) && (rep + 1 == NREP(3));
;                     const int ln = k == 15 ? l + 1 : l, jn = k == 2 ? 1 : (k == 12 ? 2 : 0), call = l * 3 + (k == 2 ? 0 : (k == 12 ? 1 : 2));
;                     const float* modn = (const float*)(ws + WS_MOD) + (size_t)ln * NBATCH * NMOD * DM;
;                     pg8::EpiResid E{(l == 0 && k == 2) ? p.x : p.out, p.out, modl + gi * DM, (rep + 1 < NREP(3)) ? 0.0f : (k == 12 ? 1.0f : 0.5f),
.LBB0_631:
	s_and_b64 vcc, exec, s[20:21]
	s_cbranch_vccz .LBB0_633
	s_add_u32 s0, s46, 0xf400000
	s_addc_u32 s1, s47, 0
	v_writelane_b32 v254, s0, 40
	s_mov_b32 s16, 0.5
	s_nop 0
	v_writelane_b32 v254, s1, 41
	s_mov_b32 s15, 2
	v_readlane_b32 s0, v254, 23
	v_readlane_b32 s1, v254, 24
	s_lshl_b32 s2, s0, 1
	v_readlane_b32 s0, v254, 36
	v_readlane_b32 s1, v254, 37
	s_xor_b64 s[0:1], s[0:1], -1
	s_mov_b32 s20, 0
	s_waitcnt lgkmcnt(0)
	v_cndmask_b32_e64 v0, 0, 1, s[0:1]
	s_movk_i32 s12, 0xb00
	s_mov_b32 s100, 0x8000
	s_mov_b32 s101, 0
	v_readfirstlane_b32 s0, v0
	s_or_b32 s0, s2, s0
	s_mul_hi_i32 s1, s0, 0x580000
	s_mul_i32 s0, s0, 0x580000
	s_add_u32 s0, s46, s0
	s_addc_u32 s1, s47, s1
	s_add_u32 s0, s0, 0x6800000
	s_addc_u32 s1, s1, 0
	v_writelane_b32 v254, s0, 42
	s_nop 1
	v_writelane_b32 v254, s1, 43
	s_mov_b64 s[0:1], 0x2000
	s_branch .LBB0_634
.LBB0_633:
	v_readlane_b32 s18, v254, 38
	s_mov_b32 s16, 1.0
	s_mov_b32 s15, 1
	s_mov_b32 s20, 2
	s_mov_b64 s[0:1], 0x1400
	s_movk_i32 s12, 0x400
	s_mov_b32 s100, 0x80
	s_mov_b32 s101, 0
	v_readlane_b32 s19, v254, 39
	s_andn2_b64 vcc, exec, s[18:19]
	s_cbranch_vccnz .LBB0_690
.LBB0_634:
	v_readlane_b32 s18, v250, 20
	s_waitcnt lgkmcnt(0)
	v_mov_b32_e32 v12, v200
	v_readlane_b32 s19, v250, 21
	s_andn2_b64 vcc, exec, s[18:19]
	v_readfirstlane_b32 s1, v12
	s_cbranch_vccnz .LBB0_689
	s_lshl_b32 vcc_hi, s12, 8
	s_cmp_eq_u32 s100, 0x80
	s_cselect_b32 vcc_lo, s12, 64
	s_cselect_b32 vcc_hi, vcc_hi, 0x4000
	v_lshlrev_b32_e32 v0, 4, v12
	v_add_u32_e32 v1, 0x2000, v0
	v_ashrrev_i32_e32 v2, 31, v1
	v_lshrrev_b32_e32 v2, 22, v2
	v_add_u32_e32 v2, v1, v2
	v_ashrrev_i32_e32 v2, 10, v2
	v_mul_i32_i24_e32 v3, 0x400, v2
	v_sub_u32_e32 v1, v1, v3
	v_lshrrev_b32_e32 v3, 4, v1
	v_bitop3_b32 v1, v3, v1, 32 bitop3:0x6c
	v_ashrrev_i32_e32 v3, 31, v1
	v_lshrrev_b32_e32 v3, 26, v3
	v_add_u32_e32 v3, v1, v3
	v_lshlrev_b32_e32 v5, 3, v2
	v_ashrrev_i32_e32 v4, 6, v3
	v_and_b32_e32 v5, -16, v5
	v_lshlrev_b32_e32 v2, 5, v2
	v_add_u32_e32 v5, v4, v5
	v_and_b32_e32 v13, 32, v2
	v_and_b32_e32 v2, 0xc0, v3
	v_and_b32_e32 v4, 3, v4
	s_mov_b32 s2, 0x7fffffe0
	v_lshrrev_b32_e32 v6, 2, v5
	v_lshlrev_b32_e32 v7, 1, v5
	v_sub_u32_e32 v1, v1, v2
	v_and_or_b32 v4, v5, s2, v4
	v_and_b32_e32 v6, 4, v6
	v_and_b32_e32 v7, 24, v7
	v_ashrrev_i16_sdwa v1, v208, sext(v1) dst_sel:DWORD dst_unused:UNUSED_PAD src0_sel:DWORD src1_sel:BYTE_0
	v_or3_b32 v4, v4, v6, v7
	v_bfe_i32 v14, v1, 0, 16
	v_mul_lo_u32 v4, v4, s12
	v_add_u32_e32 v1, v13, v14
	v_mul_lo_u32 v15, v5, s12
	v_add_lshl_u32 v158, v4, v1, 1
	v_add_lshl_u32 v160, v1, v15, 1
	s_cmp_eq_u32 s100, 0x80
	s_cbranch_scc1 .Limg_skip0
	v_lshlrev_b32_e32 v160, 4, v200
	v_add_u32_e32 v160, 0x2000, v160
.Limg_skip0:
	v_bfe_i32 v1, v12, 27, 1
	v_lshrrev_b32_e32 v1, 22, v1
	v_add_u32_e32 v1, v0, v1
	v_and_b32_e32 v1, 0xfffffc00, v1
	v_sub_u32_e32 v0, v0, v1
	v_lshrrev_b32_e32 v1, 4, v0
	v_ashrrev_i32_e32 v3, 31, v12
	v_bitop3_b32 v0, v1, v0, 32 bitop3:0x6c
	v_lshrrev_b32_e32 v3, 26, v3
	v_ashrrev_i32_e32 v1, 31, v0
	v_add_u32_e32 v3, v12, v3
	v_lshrrev_b32_e32 v1, 26, v1
	v_ashrrev_i32_e32 v3, 6, v3
	v_add_u32_e32 v1, v0, v1
	v_lshlrev_b32_e32 v4, 3, v3
	v_ashrrev_i32_e32 v2, 6, v1
	v_and_b32_e32 v4, -16, v4
	v_add_u32_e32 v4, v2, v4
	v_and_b32_e32 v1, 0xc0, v1
	v_readlane_b32 s22, v252, 23
	s_lshl_b32 s17, s12, 9
	s_ashr_i32 s13, s1, 6
	v_and_b32_e32 v2, 3, v2
	v_lshrrev_b32_e32 v5, 2, v4
	v_lshlrev_b32_e32 v6, 1, v4
	v_sub_u32_e32 v0, v0, v1
	v_readlane_b32 s23, v252, 24
	s_lshl_b32 s68, s12, 8
	s_ashr_i32 s14, s1, 8
	s_lshl_b32 s44, s13, 10
	v_and_or_b32 v2, v4, s2, v2
	v_and_b32_e32 v5, 4, v5
	v_and_b32_e32 v6, 24, v6
	v_lshlrev_b32_e32 v3, 5, v3
	v_ashrrev_i16_sdwa v0, v208, sext(v0) dst_sel:DWORD dst_unused:UNUSED_PAD src0_sel:DWORD src1_sel:BYTE_0
	s_mul_hi_i32 s19, s17, s22
	s_mul_i32 s21, s17, s22
	v_readlane_b32 s22, v254, 42
	v_or3_b32 v2, v2, v5, v6
	s_waitcnt vmcnt(0)
	v_and_b32_e32 v18, 32, v3
	v_bfe_i32 v19, v0, 0, 16
	v_readlane_b32 s23, v254, 43
	s_add_u32 s38, s22, s21
	v_mul_lo_u32 v2, v2, s12
	v_add_u32_e32 v0, v18, v19
	s_addc_u32 s39, s23, s19
	s_add_i32 s45, s44, 0
	v_add_lshl_u32 v16, v2, v0, 1
	v_readlane_b32 s18, v252, 15
	s_add_i32 m0, s45, 0x10000
	s_mul_hi_i32 s2, s17, s18
	s_mul_i32 s18, s17, s18
	global_load_lds_dwordx4 v16, s[38:39]
	s_add_i32 m0, s45, 0x12000
	v_readlane_b32 s22, v254, 40
	v_readlane_b32 s23, v254, 41
	s_add_u32 s40, s22, s18
	s_addc_u32 s41, s23, s2
	s_add_u32 s18, s38, s68
	global_load_lds_dwordx4 v158, s[38:39]
	s_addc_u32 s19, s39, 0
	s_add_i32 m0, s45, 0x14000
	s_mov_b64 s[72:73], s[46:47]
	v_mul_lo_u32 v20, v4, s12
	v_mov_b32_e32 v159, v17
	global_load_lds_dwordx4 v16, s[18:19]
	s_add_i32 m0, s45, 0x16000
	s_add_i32 s46, s45, 0x2000
	v_add_lshl_u32 v162, v0, v20, 1
	s_cmp_eq_u32 s100, 0x80
	s_cbranch_scc1 .Limg_skip1
	v_lshlrev_b32_e32 v162, 4, v200
; #define PG8_STAGE(bufoff, gbase, voff) do { _Pragma("unroll") for (int _i = 0; _i < 2; ++_i) \
;         __builtin_amdgcn_global_load_lds((const unsigned*)((const char*)(gbase) + (voff)[_i]), (LAS unsigned*)(lds + (bufoff) + ldsw + _i * 8192), 16, 0, 0); } while (0)
; #define PG8_WAIT_V(n) asm volatile("s_waitcnt vmcnt(" #n ")" ::: "memory")
; #define PG8_BAR __builtin_amdgcn_s_barrier()
; template <class Epi>
; __device__ __forceinline__ void gemm_phase(LAS unsigned char* lds, const Gemm g, const StaticOrder& S, const Epi& E) {
;     ...
;     const char* cA = (const char*)g.A + (size_t)cur.pm * tstepA + (size_t)cur.pn * ksb; const char* cB = (const char*)g.Bt + (size_t)cur.pn * bstep;
;     PG8_STAGE(PG8_SB(0, 0), cB, voffB); PG8_STAGE(PG8_SB(0, 1), cB + hstepB, voffB); PG8_STAGE(PG8_SA(0, 0), cA, voffA); PG8_STAGE(PG8_SA(0, 1), cA + hstepA, voffA);
;     if (wr == 1) PG8_BAR;
;     PG8_WAIT_V(2); PG8_BAR;
;     PG8_STAGE(PG8_SB(1, 0), cB + kstep, voffB); PG8_STAGE(PG8_SA(1, 0), cA + kstep, voffA); PG8_STAGE(PG8_SB(1, 1), cB + hstepB + kstep, voffB);
;     PG8_WAIT_V(6); PG8_BAR;
; __global__ void __launch_bounds__(NTHREADS, 2) fwd_megakernel(Params p) {
;     ...
;                     const int ln = k == 15 ? l + 1 : l, jn = k == 2 ? 1 : (k == 12 ? 2 : 0), call = l * 3 + (k == 2 ? 0 : (k == 12 ? 1 : 2));
;                     const float* modn = (const float*)(ws + WS_MOD) + (size_t)ln * NBATCH * NMOD * DM;
;                     pg8::EpiResid E{(l == 0 && k == 2) ? p.x : p.out, p.out, modl + gi * DM, (rep + 1 < NREP(3)) ? 0.0f : (k == 12 ? 1.0f : 0.5f),
;                                     fuse ? p.norm_g + (size_t)(ln * 3 + jn) * DM : nullptr, modn + (3 * jn + 1) * DM, modn + (3 * jn) * DM, (bf16_t*)(ws + WS_U), (float*)(ws + WS_XBUF),
;                                     (unsigned*)(ws + WS_BAR + 16384) + call * 128, lds + 131072 + 256};
.Limg_skip1:
	v_lshl_add_u64 v[4:5], s[18:19], 0, v[16:17]
	v_lshl_add_u64 v[6:7], s[18:19], 0, v[158:159]
	global_load_lds_dwordx4 v158, s[18:19]
	s_mov_b32 m0, s45
	s_add_u32 s18, s40, vcc_hi
	global_load_lds_dwordx4 v162, s[40:41]
	s_mov_b32 m0, s46
	s_addc_u32 s19, s41, 0
	s_add_i32 s47, s45, 0x4000
	global_load_lds_dwordx4 v160, s[40:41]
	s_mov_b32 m0, s47
	s_add_i32 s48, s45, 0x6000
	global_load_lds_dwordx4 v162, s[18:19]
	s_mov_b32 m0, s48
	v_mov_b32_e32 v163, v17
	global_load_lds_dwordx4 v160, s[18:19]
	v_mov_b32_e32 v161, v17
	s_cmp_eq_u32 s14, 1
	v_lshl_add_u64 v[0:1], s[38:39], 0, v[16:17]
	v_lshl_add_u64 v[2:3], s[38:39], 0, v[158:159]
	v_lshl_add_u64 v[8:9], s[40:41], 0, v[162:163]
	v_lshl_add_u64 v[10:11], s[40:41], 0, v[160:161]
	s_cselect_b64 s[18:19], -1, 0
	s_cmp_lg_u32 s14, 1
	s_cbranch_scc1 .LBB0_637
	s_barrier
.LBB0_637:
	s_cmp_eq_u32 s36, 15
	s_cselect_b64 s[22:23], -1, 0
	s_sub_i32 s2, s8, 49
	s_cmp_lt_u32 s2, 16
	s_cselect_b64 s[24:25], -1, 0
	v_readlane_b32 s26, v250, 7
	s_and_b64 s[24:25], s[24:25], s[22:23]
	v_readlane_b32 s27, v250, 8
	s_or_b64 s[26:27], s[26:27], s[24:25]
	s_cmp_lg_u64 s[22:23], 0
	v_readlane_b32 s22, v254, 23
	v_readlane_b32 s34, v254, 36
	v_readlane_b32 s23, v254, 24
	s_addc_u32 s2, s22, 0
	v_readlane_b32 s35, v254, 37
	s_mov_b32 s28, s22
	s_and_b64 s[22:23], s[34:35], exec
	s_cselect_b32 s24, 1, s20
	s_mul_i32 s20, s28, 3
	s_cselect_b32 s15, 0, s15
	s_add_i32 s15, s15, s20
	s_mul_i32 s21, s2, 0x48000
	s_mov_b64 s[30:31], s[72:73]
	s_mul_hi_i32 s20, s2, 0x48000
	s_add_u32 s25, s30, s21
	s_addc_u32 s28, s31, s20
	s_add_i32 s20, s8, 14
	s_cmp_lt_u32 s20, 31
	s_cselect_b64 s[20:21], -1, 0
	s_and_b64 s[20:21], s[20:21], s[34:35]
	s_and_b64 s[20:21], s[20:21], exec
	s_cselect_b32 s21, s81, s5
	s_cselect_b32 s20, s80, s4
	s_and_b64 s[22:23], s[34:35], exec
	s_cselect_b32 s0, 0x800, s0
	s_lshl_b32 s0, s0, 2
	v_readlane_b32 s22, v254, 25
	s_add_u32 s49, s22, s0
	v_readlane_b32 s0, v254, 26
	s_addc_u32 s50, s0, 0
	s_mul_i32 s0, s2, 3
	s_add_i32 s22, s0, s24
	s_ashr_i32 s23, s22, 31
	s_lshl_b64 s[22:23], s[22:23], 12
	s_add_u32 s0, s90, s22
	s_addc_u32 s2, s91, s23
	s_mulk_i32 s24, 0x3000
	s_add_u32 s51, s25, s24
	s_addc_u32 s52, s28, 0
	s_add_u32 s53, s51, 0x1000
	s_addc_u32 s54, s52, 0
	s_add_u32 s22, s30, 0xb400000
	s_addc_u32 s23, s31, 0
	s_add_u32 s24, s30, 0xf00000
	s_addc_u32 s25, s31, 0
	s_lshl_b32 s28, s15, 7
	s_ashr_i32 s29, s28, 31
	s_lshl_b64 s[28:29], s[28:29], 2
	s_add_u32 s15, s30, s28
	s_addc_u32 s28, s31, s29
	s_add_u32 s55, s15, 0x284000
	s_addc_u32 s56, s28, 0
	s_lshr_b32 s57, s12, 6
	s_add_i32 s58, s57, -2
	s_and_b64 s[26:27], s[26:27], exec
	s_cselect_b32 s27, 0, s2
	s_cselect_b32 s26, 0, s0
	s_add_i32 m0, s45, 0x18000
	v_lshl_add_u64 v[0:1], v[0:1], 0, s[70:71]
	s_waitcnt vmcnt(2)
	s_barrier
	global_load_lds_dwordx4 v[0:1], off
	v_lshl_add_u64 v[0:1], v[2:3], 0, s[70:71]
	s_add_i32 m0, s45, 0x1a000
	s_add_i32 s59, s45, 0x8000
	global_load_lds_dwordx4 v[0:1], off
	v_lshl_add_u64 v[0:1], v[8:9], 0, s[100:101]
	s_mov_b32 m0, s59
	s_add_i32 s61, s45, 0xa000
	global_load_lds_dwordx4 v[0:1], off
	v_lshl_add_u64 v[0:1], v[10:11], 0, s[100:101]
	s_mov_b32 m0, s61
	s_and_b32 s0, s13, 3
	global_load_lds_dwordx4 v[0:1], off
	s_add_i32 m0, s45, 0x1c000
	v_lshl_add_u64 v[0:1], v[4:5], 0, s[70:71]
	global_load_lds_dwordx4 v[0:1], off
	v_lshl_add_u64 v[0:1], v[6:7], 0, s[70:71]
	s_add_i32 m0, s45, 0x1e000
	s_lshl_b32 s2, s14, 13
	global_load_lds_dwordx4 v[0:1], off
	v_and_b32_e32 v1, 15, v12
	v_bfe_u32 v0, v12, 4, 2
	v_lshl_or_b32 v172, s14, 6, v1
	v_lshlrev_b32_e32 v3, 4, v0
	v_lshlrev_b32_e32 v4, 2, v172
	v_lshl_or_b32 v3, v1, 6, v3
	v_and_b32_e32 v5, 32, v4
	v_bitop3_b32 v5, v3, s2, v5 bitop3:0xde
	s_lshl_b32 s2, s0, 12
	v_lshlrev_b32_e32 v2, 3, v0
	s_cmpk_lt_u32 s1, 0x100
	v_lshl_or_b32 v174, s0, 5, v2
	s_cselect_b64 s[28:29], -1, 0
	s_lshl_b32 s0, s0, 2
	s_lshl_b32 s1, s14, 10
	s_add_i32 s0, s0, 0
	v_cmp_eq_u32_e64 s[12:13], 0, v0
	s_add_i32 s0, s0, s1
	v_add_u32_e32 v0, v15, v13
	v_lshlrev_b32_e32 v2, 4, v1
	s_add_i32 s0, s0, 0x20100
	v_add_lshl_u32 v0, v0, v14, 1
	v_mov_b32_e32 v1, v17
	v_lshlrev_b32_e32 v6, 2, v12
	s_waitcnt vmcnt(6)
	v_add_u32_e32 v164, vcc_hi, v0
	v_mov_b32_e32 v165, v1
	s_cmp_eq_u32 s100, 0x80
	s_cbranch_scc1 .Limg_skip2
	v_add_u32_e32 v164, vcc_hi, v160
.Limg_skip2:
	v_add_u32_e32 v0, v20, v18
	v_add_u32_e32 v188, s0, v2
	v_readlane_b32 s0, v252, 22
	v_and_b32_e32 v6, 32, v6
	v_add_u32_e32 v178, 0x80, v172
	v_add_u32_e32 v179, 0x90, v172
	v_add_u32_e32 v180, 0xa0, v172
	v_add_u32_e32 v181, 0xb0, v172
	v_readlane_b32 s1, v250, 22
	v_add_lshl_u32 v0, v0, v19, 1
	s_mov_b32 s36, s0
	v_readlane_b32 s0, v252, 15
	s_mov_b32 s62, 0
	v_bitop3_b32 v173, v3, s2, v6 bitop3:0xde
	v_or_b32_e32 v175, 16, v172
	v_or_b32_e32 v176, 32, v172
	v_or_b32_e32 v177, 48, v172
	v_add_u32_e32 v182, s1, v4
	v_lshl_add_u32 v183, v178, 2, s1
	v_lshl_add_u32 v184, v179, 2, s1
	v_lshl_add_u32 v185, v180, 2, s1
	v_lshl_add_u32 v186, v181, 2, s1
	v_add_u32_e32 v166, vcc_hi, v0
	v_mov_b32_e32 v167, v1
	s_cmp_eq_u32 s100, 0x80
	s_cbranch_scc1 .Limg_skip3
	v_add_u32_e32 v166, vcc_hi, v162
.Limg_skip3:
	v_add_u32_e32 v187, 0, v5
	s_mov_b32 s34, s0
	s_barrier
	s_branch .LBB0_640

; #define PG8_STAGE(bufoff, gbase, voff) do { _Pragma("unroll") for (int _i = 0; _i < 2; ++_i) \
;         __builtin_amdgcn_global_load_lds((const unsigned*)((const char*)(gbase) + (voff)[_i]), (LAS unsigned*)(lds + (bufoff) + ldsw + _i * 8192), 16, 0, 0); } while (0)
; #define PG8_LDA(dst, b, h) do { _Pragma("unroll") for (int m = 0; m < 4; ++m) _Pragma("unroll") for (int k = 0; k < 2; ++k) dst[m][k] = *(const LAS bf16x8*)(lds + PG8_SA(b, h) + aoff + m * 2048 + k * 1024); } while (0)
; #define PG8_LDB(dst, b, h) do { _Pragma("unroll") for (int n = 0; n < 2; ++n) _Pragma("unroll") for (int k = 0; k < 2; ++k) dst[n][k] = *(const LAS bf16x8*)(lds + PG8_SB(b, h) + boff + n * 2048 + k * 1024); } while (0)
; #define PG8_MMA(ai, bj, At, Bt) do { __builtin_amdgcn_s_setprio(1); _Pragma("unroll") for (int m = 0; m < 4; ++m) _Pragma("unroll") for (int n = 0; n < 2; ++n) _Pragma("unroll") for (int k = 0; k < 2; ++k) \
;         acc[ai][bj][m][n] = __builtin_amdgcn_mfma_f32_16x16x32_bf16(Bt[n][k], At[m][k], acc[ai][bj][m][n], 0, 0, 0); __builtin_amdgcn_s_setprio(0); } while (0)
; #define PG8_WAIT_V(n) asm volatile("s_waitcnt vmcnt(" #n ")" ::: "memory")
; #define PG8_WAIT_L(n) asm volatile("s_waitcnt lgkmcnt(" #n ")" ::: "memory")
; #define PG8_BAR __builtin_amdgcn_s_barrier()
; template <class Epi>
; __device__ __forceinline__ void gemm_phase(LAS unsigned char* lds, const Gemm g, const StaticOrder& S, const Epi& E) {
;     ...
;         for (int t = 0; t < nt; t += 2) {
;             const bool last = (t == nt - 2);
;             const char* a1 = cA + (size_t)(t + 1) * kstep;
;             const char* a2 = last ? nA : cA + (size_t)(t + 2) * kstep; const char* b2 = last ? nB : cB + (size_t)(t + 2) * kstep;
;             const char* a3 = a2 + kstep; const char* b3 = b2 + kstep;
;             PG8_LDB(B0, 0, 0); PG8_LDB(B1, 0, 1); PG8_SCHED; PG8_LDA(At, 0, 0); PG8_STAGE(PG8_SA(1, 1), a1 + hstepA, voffA);
;             PG8_WAIT_V(8); PG8_WAIT_L(0); PG8_BAR; PG8_MMA(0, 0, At, B0); PG8_MMA(0, 1, At, B1); PG8_BAR; PG8_SCHED;
;     ...
; #pragma unroll
;         for (int a = 0; a < 2; ++a)
; #pragma unroll
;             for (int b = 0; b < 2; ++b)
; #pragma unroll
;                 for (int m = 0; m < 4; ++m)
; #pragma unroll
;                     for (int n = 0; n < 2; ++n) acc[a][b][m][n] = (f32x4){0.f, 0.f, 0.f, 0.f};
;         cur = nxt; cA = nA; cB = nB; ++ui;
.LBB0_650:
	s_add_u32 s35, s38, 0x100
	s_addc_u32 s37, s39, 0
	s_add_u32 s38, s40, s100
	v_mov_b32_e32 v70, 0
	s_addc_u32 s39, s41, 0
	s_mov_b32 s40, 0
	v_mov_b32_e32 v71, v70
	v_mov_b32_e32 v72, v70
	v_mov_b32_e32 v73, v70
	v_mov_b32_e32 v82, v70
	v_mov_b32_e32 v83, v70
	v_mov_b32_e32 v84, v70
	v_mov_b32_e32 v85, v70
	v_mov_b32_e32 v118, v70
	v_mov_b32_e32 v119, v70
	v_mov_b32_e32 v120, v70
	v_mov_b32_e32 v121, v70
	v_mov_b32_e32 v114, v70
	v_mov_b32_e32 v115, v70
	v_mov_b32_e32 v116, v70
	v_mov_b32_e32 v117, v70
	v_mov_b32_e32 v90, v70
	v_mov_b32_e32 v91, v70
	v_mov_b32_e32 v92, v70
	v_mov_b32_e32 v93, v70
	v_mov_b32_e32 v86, v70
	v_mov_b32_e32 v87, v70
	v_mov_b32_e32 v88, v70
	v_mov_b32_e32 v89, v70
	v_mov_b32_e32 v62, v70
	v_mov_b32_e32 v63, v70
	v_mov_b32_e32 v64, v70
	v_mov_b32_e32 v65, v70
	v_mov_b32_e32 v58, v70
	v_mov_b32_e32 v59, v70
	v_mov_b32_e32 v60, v70
	v_mov_b32_e32 v61, v70
	v_mov_b32_e32 v110, v70
	v_mov_b32_e32 v111, v70
	v_mov_b32_e32 v112, v70
	v_mov_b32_e32 v113, v70
	v_mov_b32_e32 v126, v70
	v_mov_b32_e32 v127, v70
	v_mov_b32_e32 v128, v70
	v_mov_b32_e32 v129, v70
	v_mov_b32_e32 v122, v70
	v_mov_b32_e32 v123, v70
	v_mov_b32_e32 v124, v70
	v_mov_b32_e32 v125, v70
	v_mov_b32_e32 v106, v70
	v_mov_b32_e32 v107, v70
	v_mov_b32_e32 v108, v70
	v_mov_b32_e32 v109, v70
	v_mov_b32_e32 v94, v70
	v_mov_b32_e32 v95, v70
	v_mov_b32_e32 v96, v70
	v_mov_b32_e32 v97, v70
	v_mov_b32_e32 v74, v70
	v_mov_b32_e32 v75, v70
	v_mov_b32_e32 v76, v70
	v_mov_b32_e32 v77, v70
	v_mov_b32_e32 v66, v70
	v_mov_b32_e32 v67, v70
	v_mov_b32_e32 v68, v70
	v_mov_b32_e32 v69, v70
	v_mov_b32_e32 v54, v70
	v_mov_b32_e32 v55, v70
	v_mov_b32_e32 v56, v70
	v_mov_b32_e32 v57, v70
	v_mov_b32_e32 v42, v70
	v_mov_b32_e32 v43, v70
	v_mov_b32_e32 v44, v70
	v_mov_b32_e32 v45, v70
	v_mov_b32_e32 v38, v70
	v_mov_b32_e32 v39, v70
	v_mov_b32_e32 v40, v70
	v_mov_b32_e32 v41, v70
	v_mov_b32_e32 v12, v70
	v_mov_b32_e32 v13, v70
	v_mov_b32_e32 v14, v70
	v_mov_b32_e32 v15, v70
	v_mov_b32_e32 v4, v70
	v_mov_b32_e32 v5, v70
	v_mov_b32_e32 v6, v70
	v_mov_b32_e32 v7, v70
	v_mov_b32_e32 v8, v70
	v_mov_b32_e32 v9, v70
	v_mov_b32_e32 v10, v70
	v_mov_b32_e32 v11, v70
	v_mov_b32_e32 v22, v70
	v_mov_b32_e32 v23, v70
	v_mov_b32_e32 v24, v70
	v_mov_b32_e32 v25, v70
	v_mov_b32_e32 v102, v70
	v_mov_b32_e32 v103, v70
	v_mov_b32_e32 v104, v70
	v_mov_b32_e32 v105, v70
	v_mov_b32_e32 v98, v70
	v_mov_b32_e32 v99, v70
	v_mov_b32_e32 v100, v70
	v_mov_b32_e32 v101, v70
	v_mov_b32_e32 v46, v70
	v_mov_b32_e32 v47, v70
	s_waitcnt vmcnt(0)
	v_mov_b32_e32 v48, v70
	v_mov_b32_e32 v49, v70
	v_mov_b32_e32 v30, v70
	v_mov_b32_e32 v31, v70
	v_mov_b32_e32 v32, v70
	v_mov_b32_e32 v33, v70
	v_mov_b32_e32 v18, v70
	v_mov_b32_e32 v19, v70
	v_mov_b32_e32 v20, v70
	v_mov_b32_e32 v21, v70
	v_mov_b32_e32 v0, v70
	v_mov_b32_e32 v1, v70
	v_mov_b32_e32 v2, v70
	v_mov_b32_e32 v3, v70
	v_mov_b32_e32 v34, v70
	v_mov_b32_e32 v35, v70
	v_mov_b32_e32 v36, v70
	v_mov_b32_e32 v37, v70
	v_mov_b32_e32 v26, v70
	v_mov_b32_e32 v27, v70
	v_mov_b32_e32 v28, v70
	v_mov_b32_e32 v29, v70
	v_mov_b32_e32 v78, v70
	v_mov_b32_e32 v79, v70
	v_mov_b32_e32 v80, v70
	v_mov_b32_e32 v81, v70
	v_mov_b32_e32 v50, v70
	v_mov_b32_e32 v51, v70
	v_mov_b32_e32 v52, v70
	v_mov_b32_e32 v53, v70
.LBB0_651:
	s_add_i32 s42, s40, 2
	s_add_u32 s2, s38, s100
	s_addc_u32 s41, s39, 0
	s_add_i32 s43, 0, 0x10000
	s_cmp_eq_u32 s58, s40
	s_cselect_b32 s41, s1, s41
	s_cselect_b32 s40, s0, s2
	s_cselect_b32 s67, s31, s37
	s_cselect_b32 s66, s30, s35
	s_add_i32 s2, 0, 0x14000
	v_add_u32_e32 v142, s43, v173
	v_add_u32_e32 v168, s2, v173
	ds_read_b128 v[130:133], v142
	ds_read_b128 v[134:137], v142 offset:1024
	ds_read_b128 v[138:141], v142 offset:2048
	ds_read_b128 v[142:145], v142 offset:3072
	ds_read_b128 v[146:149], v168
	ds_read_b128 v[150:153], v168 offset:1024
	ds_read_b128 v[154:157], v168 offset:2048
	ds_read_b128 v[168:171], v168 offset:3072
	v_lshl_add_u64 v[198:199], s[38:39], 0, v[166:167]
	s_add_i32 m0, s45, 0xc000
	ds_read_b128 v[190:193], v187
	ds_read_b128 v[194:197], v187 offset:1024
	ds_read_b128 v[218:221], v187 offset:2048
	ds_read_b128 v[222:225], v187 offset:3072
	ds_read_b128 v[226:229], v187 offset:4096
	ds_read_b128 v[230:233], v187 offset:5120
	ds_read_b128 v[234:237], v187 offset:6144
	ds_read_b128 v[238:241], v187 offset:7168
	global_load_lds_dwordx4 v[198:199], off
	v_lshl_add_u64 v[198:199], s[38:39], 0, v[164:165]
	s_add_i32 m0, s45, 0xe000
	s_nop 0
	global_load_lds_dwordx4 v[198:199], off
	s_waitcnt vmcnt(8)
	s_waitcnt lgkmcnt(0)
	s_barrier
; #define PG8_STAGE(bufoff, gbase, voff) do { _Pragma("unroll") for (int _i = 0; _i < 2; ++_i) \
;         __builtin_amdgcn_global_load_lds((const unsigned*)((const char*)(gbase) + (voff)[_i]), (LAS unsigned*)(lds + (bufoff) + ldsw + _i * 8192), 16, 0, 0); } while (0)
; #define PG8_LDA(dst, b, h) do { _Pragma("unroll") for (int m = 0; m < 4; ++m) _Pragma("unroll") for (int k = 0; k < 2; ++k) dst[m][k] = *(const LAS bf16x8*)(lds + PG8_SA(b, h) + aoff + m * 2048 + k * 1024); } while (0)
; #define PG8_MMA(ai, bj, At, Bt) do { __builtin_amdgcn_s_setprio(1); _Pragma("unroll") for (int m = 0; m < 4; ++m) _Pragma("unroll") for (int n = 0; n < 2; ++n) _Pragma("unroll") for (int k = 0; k < 2; ++k) \
;         acc[ai][bj][m][n] = __builtin_amdgcn_mfma_f32_16x16x32_bf16(Bt[n][k], At[m][k], acc[ai][bj][m][n], 0, 0, 0); __builtin_amdgcn_s_setprio(0); } while (0)
; #define PG8_WAIT_V(n) asm volatile("s_waitcnt vmcnt(" #n ")" ::: "memory")
; #define PG8_WAIT_L(n) asm volatile("s_waitcnt lgkmcnt(" #n ")" ::: "memory")
; #define PG8_BAR __builtin_amdgcn_s_barrier()
; #define PG8_SCHED __builtin_amdgcn_sched_barrier(0)
; template <class Epi>
; __device__ __forceinline__ void gemm_phase(LAS unsigned char* lds, const Gemm g, const StaticOrder& S, const Epi& E) {
;     ...
;             PG8_WAIT_V(8); PG8_WAIT_L(0); PG8_BAR; PG8_MMA(0, 0, At, B0); PG8_MMA(0, 1, At, B1); PG8_BAR; PG8_SCHED;
;             PG8_LDA(At, 0, 1); PG8_STAGE(PG8_SB(0, 0), b2, voffB); PG8_STAGE(PG8_SB(0, 1), b2 + hstepB, voffB); PG8_STAGE(PG8_SA(0, 0), a2, voffA);
;             PG8_WAIT_V(8); PG8_WAIT_L(0); PG8_BAR; PG8_MMA(1, 0, At, B0); PG8_MMA(1, 1, At, B1); PG8_BAR; PG8_SCHED;
	s_setprio 1
	s_waitcnt lgkmcnt(0)
	v_mfma_f32_16x16x32_bf16 v[50:53], v[130:133], v[190:193], v[50:53]
	v_mfma_f32_16x16x32_bf16 v[78:81], v[138:141], v[190:193], v[78:81]
	v_mfma_f32_16x16x32_bf16 v[26:29], v[130:133], v[218:221], v[26:29]
	v_mfma_f32_16x16x32_bf16 v[34:37], v[138:141], v[218:221], v[34:37]
	v_mfma_f32_16x16x32_bf16 v[0:3], v[130:133], v[226:229], v[0:3]
	v_mfma_f32_16x16x32_bf16 v[18:21], v[138:141], v[226:229], v[18:21]
	v_mfma_f32_16x16x32_bf16 v[30:33], v[130:133], v[234:237], v[30:33]
	v_mfma_f32_16x16x32_bf16 v[46:49], v[138:141], v[234:237], v[46:49]
	v_mfma_f32_16x16x32_bf16 v[50:53], v[134:137], v[194:197], v[50:53]
	v_mfma_f32_16x16x32_bf16 v[78:81], v[142:145], v[194:197], v[78:81]
	v_mfma_f32_16x16x32_bf16 v[26:29], v[134:137], v[222:225], v[26:29]
	v_mfma_f32_16x16x32_bf16 v[34:37], v[142:145], v[222:225], v[34:37]
	v_mfma_f32_16x16x32_bf16 v[0:3], v[134:137], v[230:233], v[0:3]
	v_mfma_f32_16x16x32_bf16 v[18:21], v[142:145], v[230:233], v[18:21]
	v_mfma_f32_16x16x32_bf16 v[30:33], v[134:137], v[238:241], v[30:33]
	v_mfma_f32_16x16x32_bf16 v[46:49], v[142:145], v[238:241], v[46:49]
	s_setprio 0
	s_setprio 1
	v_mfma_f32_16x16x32_bf16 v[98:101], v[146:149], v[190:193], v[98:101]
	v_mfma_f32_16x16x32_bf16 v[102:105], v[154:157], v[190:193], v[102:105]
	v_mfma_f32_16x16x32_bf16 v[22:25], v[146:149], v[218:221], v[22:25]
	v_mfma_f32_16x16x32_bf16 v[8:11], v[154:157], v[218:221], v[8:11]
	v_mfma_f32_16x16x32_bf16 v[4:7], v[146:149], v[226:229], v[4:7]
	v_mfma_f32_16x16x32_bf16 v[12:15], v[154:157], v[226:229], v[12:15]
	v_mfma_f32_16x16x32_bf16 v[38:41], v[146:149], v[234:237], v[38:41]
	v_mfma_f32_16x16x32_bf16 v[42:45], v[154:157], v[234:237], v[42:45]
	v_mfma_f32_16x16x32_bf16 v[98:101], v[150:153], v[194:197], v[98:101]
	v_mfma_f32_16x16x32_bf16 v[102:105], v[168:171], v[194:197], v[102:105]
	v_mfma_f32_16x16x32_bf16 v[22:25], v[150:153], v[222:225], v[22:25]
	v_mfma_f32_16x16x32_bf16 v[8:11], v[168:171], v[222:225], v[8:11]
	v_mfma_f32_16x16x32_bf16 v[4:7], v[150:153], v[230:233], v[4:7]
	v_mfma_f32_16x16x32_bf16 v[12:15], v[168:171], v[230:233], v[12:15]
	v_mfma_f32_16x16x32_bf16 v[38:41], v[150:153], v[238:241], v[38:41]
	v_mfma_f32_16x16x32_bf16 v[42:45], v[168:171], v[238:241], v[42:45]
	s_setprio 0
	s_barrier
	s_add_i32 s43, s43, s44
	v_lshl_add_u64 v[198:199], s[66:67], 0, v[16:17]
	s_mov_b32 m0, s43
	ds_read_b128 v[190:193], v187 offset:16384
	ds_read_b128 v[194:197], v187 offset:17408
	ds_read_b128 v[218:221], v187 offset:18432
	ds_read_b128 v[222:225], v187 offset:19456
	ds_read_b128 v[226:229], v187 offset:20480
	ds_read_b128 v[230:233], v187 offset:21504
	ds_read_b128 v[234:237], v187 offset:22528
	ds_read_b128 v[238:241], v187 offset:23552
	global_load_lds_dwordx4 v[198:199], off
	s_add_i32 m0, s43, 0x2000
	v_lshl_add_u64 v[242:243], s[66:67], 0, v[158:159]
	s_add_u32 s66, s66, s68
	s_addc_u32 s67, s67, 0
	s_add_i32 s2, s2, s44
	global_load_lds_dwordx4 v[242:243], off
	v_lshl_add_u64 v[244:245], s[66:67], 0, v[16:17]
	s_mov_b32 m0, s2
	v_lshl_add_u64 v[246:247], s[66:67], 0, v[158:159]
	global_load_lds_dwordx4 v[244:245], off
	s_add_i32 m0, s2, 0x2000
	v_lshl_add_u64 v[248:249], s[40:41], 0, v[162:163]
	global_load_lds_dwordx4 v[246:247], off
	s_mov_b32 m0, s45
	v_lshl_add_u64 v[204:205], s[40:41], 0, v[160:161]
	global_load_lds_dwordx4 v[248:249], off
	s_mov_b32 m0, s46
	s_nop 0
	global_load_lds_dwordx4 v[204:205], off
	s_waitcnt vmcnt(8)
	s_waitcnt lgkmcnt(0)
	s_barrier
	s_setprio 1
	s_waitcnt lgkmcnt(0)
	v_mfma_f32_16x16x32_bf16 v[54:57], v[130:133], v[190:193], v[54:57]
	v_mfma_f32_16x16x32_bf16 v[66:69], v[138:141], v[190:193], v[66:69]
	v_mfma_f32_16x16x32_bf16 v[74:77], v[130:133], v[218:221], v[74:77]
	v_mfma_f32_16x16x32_bf16 v[94:97], v[138:141], v[218:221], v[94:97]
	v_mfma_f32_16x16x32_bf16 v[106:109], v[130:133], v[226:229], v[106:109]
	v_mfma_f32_16x16x32_bf16 v[122:125], v[138:141], v[226:229], v[122:125]
	v_mfma_f32_16x16x32_bf16 v[126:129], v[130:133], v[234:237], v[126:129]
	v_mfma_f32_16x16x32_bf16 v[110:113], v[138:141], v[234:237], v[110:113]
	v_mfma_f32_16x16x32_bf16 v[54:57], v[134:137], v[194:197], v[54:57]
	v_mfma_f32_16x16x32_bf16 v[66:69], v[142:145], v[194:197], v[66:69]
	v_mfma_f32_16x16x32_bf16 v[74:77], v[134:137], v[222:225], v[74:77]
	v_mfma_f32_16x16x32_bf16 v[94:97], v[142:145], v[222:225], v[94:97]
	v_mfma_f32_16x16x32_bf16 v[106:109], v[134:137], v[230:233], v[106:109]
	v_mfma_f32_16x16x32_bf16 v[122:125], v[142:145], v[230:233], v[122:125]
	v_mfma_f32_16x16x32_bf16 v[126:129], v[134:137], v[238:241], v[126:129]
	v_mfma_f32_16x16x32_bf16 v[110:113], v[142:145], v[238:241], v[110:113]
	s_setprio 0
	s_setprio 1
	v_mfma_f32_16x16x32_bf16 v[58:61], v[146:149], v[190:193], v[58:61]
	v_mfma_f32_16x16x32_bf16 v[62:65], v[154:157], v[190:193], v[62:65]
	v_mfma_f32_16x16x32_bf16 v[86:89], v[146:149], v[218:221], v[86:89]
	v_mfma_f32_16x16x32_bf16 v[90:93], v[154:157], v[218:221], v[90:93]
	v_mfma_f32_16x16x32_bf16 v[114:117], v[146:149], v[226:229], v[114:117]
	v_mfma_f32_16x16x32_bf16 v[118:121], v[154:157], v[226:229], v[118:121]
	v_mfma_f32_16x16x32_bf16 v[82:85], v[146:149], v[234:237], v[82:85]
	v_mfma_f32_16x16x32_bf16 v[70:73], v[154:157], v[234:237], v[70:73]
	v_mfma_f32_16x16x32_bf16 v[58:61], v[150:153], v[194:197], v[58:61]
	v_mfma_f32_16x16x32_bf16 v[62:65], v[168:171], v[194:197], v[62:65]
	v_mfma_f32_16x16x32_bf16 v[86:89], v[150:153], v[222:225], v[86:89]
	v_mfma_f32_16x16x32_bf16 v[90:93], v[168:171], v[222:225], v[90:93]
	v_mfma_f32_16x16x32_bf16 v[114:117], v[150:153], v[230:233], v[114:117]
	v_mfma_f32_16x16x32_bf16 v[118:121], v[168:171], v[230:233], v[118:121]
	v_mfma_f32_16x16x32_bf16 v[82:85], v[150:153], v[238:241], v[82:85]
	v_mfma_f32_16x16x32_bf16 v[70:73], v[168:171], v[238:241], v[70:73]
	s_setprio 0
	s_barrier
; #define PG8_STAGE(bufoff, gbase, voff) do { _Pragma("unroll") for (int _i = 0; _i < 2; ++_i) \
;         __builtin_amdgcn_global_load_lds((const unsigned*)((const char*)(gbase) + (voff)[_i]), (LAS unsigned*)(lds + (bufoff) + ldsw + _i * 8192), 16, 0, 0); } while (0)
; #define PG8_LDA(dst, b, h) do { _Pragma("unroll") for (int m = 0; m < 4; ++m) _Pragma("unroll") for (int k = 0; k < 2; ++k) dst[m][k] = *(const LAS bf16x8*)(lds + PG8_SA(b, h) + aoff + m * 2048 + k * 1024); } while (0)
; #define PG8_LDB(dst, b, h) do { _Pragma("unroll") for (int n = 0; n < 2; ++n) _Pragma("unroll") for (int k = 0; k < 2; ++k) dst[n][k] = *(const LAS bf16x8*)(lds + PG8_SB(b, h) + boff + n * 2048 + k * 1024); } while (0)
; #define PG8_MMA(ai, bj, At, Bt) do { __builtin_amdgcn_s_setprio(1); _Pragma("unroll") for (int m = 0; m < 4; ++m) _Pragma("unroll") for (int n = 0; n < 2; ++n) _Pragma("unroll") for (int k = 0; k < 2; ++k) \
;         acc[ai][bj][m][n] = __builtin_amdgcn_mfma_f32_16x16x32_bf16(Bt[n][k], At[m][k], acc[ai][bj][m][n], 0, 0, 0); __builtin_amdgcn_s_setprio(0); } while (0)
; #define PG8_WAIT_V(n) asm volatile("s_waitcnt vmcnt(" #n ")" ::: "memory")
; #define PG8_WAIT_L(n) asm volatile("s_waitcnt lgkmcnt(" #n ")" ::: "memory")
; #define PG8_BAR __builtin_amdgcn_s_barrier()
; #define PG8_SCHED __builtin_amdgcn_sched_barrier(0)
; template <class Epi>
; __device__ __forceinline__ void gemm_phase(LAS unsigned char* lds, const Gemm g, const StaticOrder& S, const Epi& E) {
;     ...
;             PG8_LDB(B0, 1, 0); PG8_LDB(B1, 1, 1); PG8_SCHED; PG8_LDA(At, 1, 0); PG8_STAGE(PG8_SA(0, 1), a2 + hstepA, voffA);
;             PG8_WAIT_V(8); PG8_WAIT_L(0); PG8_BAR; PG8_MMA(0, 0, At, B0); PG8_MMA(0, 1, At, B1); PG8_BAR; PG8_SCHED;
	s_add_i32 s2, 0, 0x18000
	s_add_i32 s43, 0, 0x1c000
	v_add_u32_e32 v142, s2, v173
	v_add_u32_e32 v168, s43, v173
	ds_read_b128 v[130:133], v142
	ds_read_b128 v[134:137], v142 offset:1024
	ds_read_b128 v[138:141], v142 offset:2048
	ds_read_b128 v[142:145], v142 offset:3072
	ds_read_b128 v[146:149], v168
	ds_read_b128 v[150:153], v168 offset:1024
	ds_read_b128 v[154:157], v168 offset:2048
	ds_read_b128 v[168:171], v168 offset:3072
	s_cmp_eq_u32 s100, 0x80
	s_cselect_b32 vcc_lo, s68, 0x4000
	s_add_u32 s40, s40, vcc_lo
	s_addc_u32 s41, s41, 0
	s_mov_b32 m0, s47
	v_lshl_add_u64 v[202:203], s[40:41], 0, v[162:163]
	ds_read_b128 v[190:193], v187 offset:32768
	ds_read_b128 v[194:197], v187 offset:33792
	ds_read_b128 v[218:221], v187 offset:34816
	ds_read_b128 v[222:225], v187 offset:35840
	ds_read_b128 v[226:229], v187 offset:36864
	ds_read_b128 v[230:233], v187 offset:37888
	ds_read_b128 v[234:237], v187 offset:38912
	ds_read_b128 v[238:241], v187 offset:39936
	global_load_lds_dwordx4 v[202:203], off
	v_lshl_add_u64 v[202:203], s[40:41], 0, v[160:161]
	s_mov_b32 m0, s48
	s_nop 0
	global_load_lds_dwordx4 v[202:203], off
	s_waitcnt vmcnt(8)
	s_waitcnt lgkmcnt(0)
	s_barrier
	s_setprio 1
	s_waitcnt lgkmcnt(0)
	v_mfma_f32_16x16x32_bf16 v[50:53], v[130:133], v[190:193], v[50:53]
	v_mfma_f32_16x16x32_bf16 v[78:81], v[138:141], v[190:193], v[78:81]
	v_mfma_f32_16x16x32_bf16 v[26:29], v[130:133], v[218:221], v[26:29]
	v_mfma_f32_16x16x32_bf16 v[34:37], v[138:141], v[218:221], v[34:37]
	v_mfma_f32_16x16x32_bf16 v[0:3], v[130:133], v[226:229], v[0:3]
	v_mfma_f32_16x16x32_bf16 v[18:21], v[138:141], v[226:229], v[18:21]
	v_mfma_f32_16x16x32_bf16 v[30:33], v[130:133], v[234:237], v[30:33]
	v_mfma_f32_16x16x32_bf16 v[46:49], v[138:141], v[234:237], v[46:49]
	v_mfma_f32_16x16x32_bf16 v[50:53], v[134:137], v[194:197], v[50:53]
	v_mfma_f32_16x16x32_bf16 v[78:81], v[142:145], v[194:197], v[78:81]
	v_mfma_f32_16x16x32_bf16 v[26:29], v[134:137], v[222:225], v[26:29]
	v_mfma_f32_16x16x32_bf16 v[34:37], v[142:145], v[222:225], v[34:37]
	v_mfma_f32_16x16x32_bf16 v[0:3], v[134:137], v[230:233], v[0:3]
	v_mfma_f32_16x16x32_bf16 v[18:21], v[142:145], v[230:233], v[18:21]
	v_mfma_f32_16x16x32_bf16 v[30:33], v[134:137], v[238:241], v[30:33]
	v_mfma_f32_16x16x32_bf16 v[46:49], v[142:145], v[238:241], v[46:49]
	s_setprio 0
	s_setprio 1
	v_mfma_f32_16x16x32_bf16 v[98:101], v[146:149], v[190:193], v[98:101]
	v_mfma_f32_16x16x32_bf16 v[102:105], v[154:157], v[190:193], v[102:105]
	v_mfma_f32_16x16x32_bf16 v[22:25], v[146:149], v[218:221], v[22:25]
	v_mfma_f32_16x16x32_bf16 v[8:11], v[154:157], v[218:221], v[8:11]
	v_mfma_f32_16x16x32_bf16 v[4:7], v[146:149], v[226:229], v[4:7]
	v_mfma_f32_16x16x32_bf16 v[12:15], v[154:157], v[226:229], v[12:15]
	v_mfma_f32_16x16x32_bf16 v[38:41], v[146:149], v[234:237], v[38:41]
	v_mfma_f32_16x16x32_bf16 v[42:45], v[154:157], v[234:237], v[42:45]
	v_mfma_f32_16x16x32_bf16 v[98:101], v[150:153], v[194:197], v[98:101]
	v_mfma_f32_16x16x32_bf16 v[102:105], v[168:171], v[194:197], v[102:105]
	v_mfma_f32_16x16x32_bf16 v[22:25], v[150:153], v[222:225], v[22:25]
	v_mfma_f32_16x16x32_bf16 v[8:11], v[168:171], v[222:225], v[8:11]
	v_mfma_f32_16x16x32_bf16 v[4:7], v[150:153], v[230:233], v[4:7]
	v_mfma_f32_16x16x32_bf16 v[12:15], v[168:171], v[230:233], v[12:15]
	v_mfma_f32_16x16x32_bf16 v[38:41], v[150:153], v[238:241], v[38:41]
	v_mfma_f32_16x16x32_bf16 v[42:45], v[168:171], v[238:241], v[42:45]
	s_setprio 0
	s_barrier
; #define PG8_STAGE(bufoff, gbase, voff) do { _Pragma("unroll") for (int _i = 0; _i < 2; ++_i) \
;         __builtin_amdgcn_global_load_lds((const unsigned*)((const char*)(gbase) + (voff)[_i]), (LAS unsigned*)(lds + (bufoff) + ldsw + _i * 8192), 16, 0, 0); } while (0)
; #define PG8_LDA(dst, b, h) do { _Pragma("unroll") for (int m = 0; m < 4; ++m) _Pragma("unroll") for (int k = 0; k < 2; ++k) dst[m][k] = *(const LAS bf16x8*)(lds + PG8_SA(b, h) + aoff + m * 2048 + k * 1024); } while (0)
; #define PG8_MMA(ai, bj, At, Bt) do { __builtin_amdgcn_s_setprio(1); _Pragma("unroll") for (int m = 0; m < 4; ++m) _Pragma("unroll") for (int n = 0; n < 2; ++n) _Pragma("unroll") for (int k = 0; k < 2; ++k) \
;         acc[ai][bj][m][n] = __builtin_amdgcn_mfma_f32_16x16x32_bf16(Bt[n][k], At[m][k], acc[ai][bj][m][n], 0, 0, 0); __builtin_amdgcn_s_setprio(0); } while (0)
; #define PG8_WAIT_V(n) asm volatile("s_waitcnt vmcnt(" #n ")" ::: "memory")
; #define PG8_WAIT_L(n) asm volatile("s_waitcnt lgkmcnt(" #n ")" ::: "memory")
; #define PG8_BAR __builtin_amdgcn_s_barrier()
; #define PG8_SCHED __builtin_amdgcn_sched_barrier(0)
; template <class Epi>
; __device__ __forceinline__ void gemm_phase(LAS unsigned char* lds, const Gemm g, const StaticOrder& S, const Epi& E) {
;     ...
;             PG8_LDA(At, 1, 1); PG8_STAGE(PG8_SB(1, 0), b3, voffB); PG8_STAGE(PG8_SB(1, 1), b3 + hstepB, voffB); PG8_STAGE(PG8_SA(1, 0), a3, voffA);
;             PG8_WAIT_V(8); PG8_WAIT_L(0); PG8_BAR; PG8_MMA(1, 0, At, B0); PG8_MMA(1, 1, At, B1); PG8_BAR; PG8_SCHED;
;         }
	s_add_i32 s2, s2, s44
	v_lshl_add_u64 v[198:199], v[198:199], 0, s[70:71]
	s_mov_b32 m0, s2
	ds_read_b128 v[190:193], v187 offset:49152
	ds_read_b128 v[194:197], v187 offset:50176
	ds_read_b128 v[218:221], v187 offset:51200
	ds_read_b128 v[222:225], v187 offset:52224
	ds_read_b128 v[226:229], v187 offset:53248
	ds_read_b128 v[230:233], v187 offset:54272
	ds_read_b128 v[234:237], v187 offset:55296
	ds_read_b128 v[238:241], v187 offset:56320
	global_load_lds_dwordx4 v[198:199], off
	v_lshl_add_u64 v[198:199], v[242:243], 0, s[70:71]
	s_add_i32 m0, s2, 0x2000
	s_add_i32 s2, s43, s44
	global_load_lds_dwordx4 v[198:199], off
	v_lshl_add_u64 v[198:199], v[244:245], 0, s[70:71]
	s_mov_b32 m0, s2
	s_nop 0
	global_load_lds_dwordx4 v[198:199], off
	v_lshl_add_u64 v[198:199], v[246:247], 0, s[70:71]
	s_add_i32 m0, s2, 0x2000
	s_nop 0
	global_load_lds_dwordx4 v[198:199], off
	v_lshl_add_u64 v[198:199], v[248:249], 0, s[100:101]
	s_mov_b32 m0, s59
	s_nop 0
	global_load_lds_dwordx4 v[198:199], off
	v_lshl_add_u64 v[198:199], v[204:205], 0, s[100:101]
	s_mov_b32 m0, s61
	s_nop 0
	global_load_lds_dwordx4 v[198:199], off
	s_waitcnt vmcnt(8)
	s_waitcnt lgkmcnt(0)
	s_barrier
	s_setprio 1
	s_waitcnt lgkmcnt(0)
	v_mfma_f32_16x16x32_bf16 v[54:57], v[130:133], v[190:193], v[54:57]
	v_mfma_f32_16x16x32_bf16 v[66:69], v[138:141], v[190:193], v[66:69]
	v_mfma_f32_16x16x32_bf16 v[74:77], v[130:133], v[218:221], v[74:77]
	v_mfma_f32_16x16x32_bf16 v[94:97], v[138:141], v[218:221], v[94:97]
	v_mfma_f32_16x16x32_bf16 v[106:109], v[130:133], v[226:229], v[106:109]
	v_mfma_f32_16x16x32_bf16 v[122:125], v[138:141], v[226:229], v[122:125]
	v_mfma_f32_16x16x32_bf16 v[126:129], v[130:133], v[234:237], v[126:129]
	v_mfma_f32_16x16x32_bf16 v[110:113], v[138:141], v[234:237], v[110:113]
	v_mfma_f32_16x16x32_bf16 v[54:57], v[134:137], v[194:197], v[54:57]
	v_mfma_f32_16x16x32_bf16 v[66:69], v[142:145], v[194:197], v[66:69]
	v_mfma_f32_16x16x32_bf16 v[74:77], v[134:137], v[222:225], v[74:77]
	v_mfma_f32_16x16x32_bf16 v[94:97], v[142:145], v[222:225], v[94:97]
	v_mfma_f32_16x16x32_bf16 v[106:109], v[134:137], v[230:233], v[106:109]
	v_mfma_f32_16x16x32_bf16 v[122:125], v[142:145], v[230:233], v[122:125]
	v_mfma_f32_16x16x32_bf16 v[126:129], v[134:137], v[238:241], v[126:129]
	v_mfma_f32_16x16x32_bf16 v[110:113], v[142:145], v[238:241], v[110:113]
	s_setprio 0
	s_setprio 1
	v_mfma_f32_16x16x32_bf16 v[58:61], v[146:149], v[190:193], v[58:61]
	v_mfma_f32_16x16x32_bf16 v[62:65], v[154:157], v[190:193], v[62:65]
	v_mfma_f32_16x16x32_bf16 v[86:89], v[146:149], v[218:221], v[86:89]
	v_mfma_f32_16x16x32_bf16 v[90:93], v[154:157], v[218:221], v[90:93]
	v_mfma_f32_16x16x32_bf16 v[114:117], v[146:149], v[226:229], v[114:117]
	v_mfma_f32_16x16x32_bf16 v[118:121], v[154:157], v[226:229], v[118:121]
	v_mfma_f32_16x16x32_bf16 v[82:85], v[146:149], v[234:237], v[82:85]
	v_mfma_f32_16x16x32_bf16 v[70:73], v[154:157], v[234:237], v[70:73]
	v_mfma_f32_16x16x32_bf16 v[58:61], v[150:153], v[194:197], v[58:61]
	v_mfma_f32_16x16x32_bf16 v[62:65], v[168:171], v[194:197], v[62:65]
	v_mfma_f32_16x16x32_bf16 v[86:89], v[150:153], v[222:225], v[86:89]
	v_mfma_f32_16x16x32_bf16 v[90:93], v[168:171], v[222:225], v[90:93]
	v_mfma_f32_16x16x32_bf16 v[114:117], v[150:153], v[230:233], v[114:117]
	v_mfma_f32_16x16x32_bf16 v[118:121], v[168:171], v[230:233], v[118:121]
	v_mfma_f32_16x16x32_bf16 v[82:85], v[150:153], v[238:241], v[82:85]
	v_mfma_f32_16x16x32_bf16 v[70:73], v[168:171], v[238:241], v[70:73]
	s_setprio 0
	s_barrier
	s_add_u32 s35, s35, 0x100
	s_addc_u32 s37, s37, 0
	s_lshl_b32 vcc_lo, s100, 1
	s_add_u32 s38, s38, vcc_lo
	s_addc_u32 s39, s39, 0
	s_cmp_ge_u32 s42, s57
	s_mov_b32 s40, s42
	s_cbranch_scc0 .LBB0_651
	s_and_b64 vcc, exec, s[28:29]
	s_cbranch_vccz .LBB0_654
	s_barrier

; __device__ __forceinline__ unsigned cvtpk(float lo, float hi) { f32x2 v = {lo, hi}; bf16x2_t b = __builtin_convertvector(v, bf16x2_t); return __builtin_bit_cast(unsigned, b); }
; __device__ __forceinline__ float silu_f(float g) { return g * __builtin_amdgcn_rcpf(1.0f + fast_exp2(-g * LOG2E)); }
;     __device__ __forceinline__ void operator()(const f32x4 (&acc)[2][2][4][2], const Unit& u, int wr, int wc, int fr, int fq) const {
;         const int row0 = u.pm * BM + wr * 64 + fr, col0 = u.pn * HALF + wc * 32 + 8 * fq;
; #pragma unroll
;         for (int ai = 0; ai < 2; ++ai)
; #pragma unroll
;             for (int m = 0; m < 4; ++m) { bf16_t* rowp = O + (size_t)(row0 + ai * HALF + m * 16) * DFF + col0;
;                 float r[8];
; #pragma unroll
;                 for (int n = 0; n < 2; ++n)
; #pragma unroll
;                     for (int e = 0; e < 4; ++e) r[n * 4 + e] = silu_f(acc[ai][0][m][n][e]) * acc[ai][1][m][n][e];
;                 u32x4 w; w.x = cvtpk(r[0], r[1]); w.y = cvtpk(r[2], r[3]); w.z = cvtpk(r[4], r[5]); w.w = cvtpk(r[6], r[7]);
;                 *(u32x4*)rowp = w; }
.LBB0_704:
	v_mul_f32_e32 v140, 0xbfb8aa3b, v126
	v_exp_f32_e32 v140, v140
	v_mul_f32_e32 v141, 0xbfb8aa3b, v127
	v_exp_f32_e32 v141, v141
	v_mul_f32_e32 v147, 0xbfb8aa3b, v128
	v_add_f32_e32 v140, 1.0, v140
	v_rcp_f32_e32 v150, v140
	v_add_f32_e32 v140, 1.0, v141
	v_rcp_f32_e32 v151, v140
	v_exp_f32_e32 v147, v147
	v_lshl_or_b32 v148, s46, 7, v144
	v_lshl_add_u32 v146, s47, 8, v142
	v_pk_mul_f32 v[126:127], v[126:127], v[150:151]
	v_mul_f32_e32 v150, 0xbfb8aa3b, v129
	v_exp_f32_e32 v150, v150
	v_pk_mul_f32 v[118:119], v[126:127], v[118:119]
	v_add_f32_e32 v126, 1.0, v147
	v_mul_f32_e32 v147, 0xbfb8aa3b, v122
	v_add_f32_e32 v127, 1.0, v150
	v_rcp_f32_e32 v126, v126
	v_rcp_f32_e32 v127, v127
	v_exp_f32_e32 v147, v147
	v_mul_f32_e32 v150, 0xbfb8aa3b, v123
	v_exp_f32_e32 v150, v150
	v_pk_mul_f32 v[126:127], v[128:129], v[126:127]
	v_add_f32_e32 v128, 1.0, v147
	v_mul_f32_e32 v147, 0xbfb8aa3b, v124
	v_add_f32_e32 v129, 1.0, v150
	v_exp_f32_e32 v147, v147
	v_mul_f32_e32 v150, 0xbfb8aa3b, v125
	v_exp_f32_e32 v151, v150
	v_rcp_f32_e32 v128, v128
	v_add_f32_e32 v147, 1.0, v147
	v_rcp_f32_e32 v129, v129
	v_rcp_f32_e32 v150, v147
	v_add_f32_e32 v147, 1.0, v151
	v_rcp_f32_e32 v151, v147
	v_pk_mul_f32 v[122:123], v[122:123], v[128:129]
	v_pk_mul_f32 v[120:121], v[126:127], v[120:121]
	v_pk_mul_f32 v[122:123], v[122:123], v[114:115]
	v_pk_mul_f32 v[114:115], v[124:125], v[150:151]
	v_ashrrev_i32_e32 v149, 31, v148
	v_pk_mul_f32 v[124:125], v[114:115], v[116:117]
	v_cvt_pk_bf16_f32 v117, v120, v121
	v_mul_f32_e32 v120, 0xbfb8aa3b, v110
	v_mul_f32_e32 v121, 0xbfb8aa3b, v111
	v_exp_f32_e32 v120, v120
	v_exp_f32_e32 v121, v121
	v_mov_b64_e32 v[140:141], s[14:15]
	s_movk_i32 s2, 0x80
	v_mad_i64_i32 v[152:153], s[26:27], v146, s2, v[140:141]
	v_and_b32_e32 v114, 15, v142
	v_lshlrev_b32_e32 v115, 6, v114
	v_and_b32_e32 v149, 24, v144
	v_lshl_or_b32 v115, v149, 1, v115
	v_and_b32_e32 v149, 8, v114
	v_lshlrev_b32_e32 v149, 2, v149
	v_xor_b32_e32 v115, v115, v149
	v_lshlrev_b32_e32 v114, 7, v114
	v_sub_u32_e32 v114, v115, v114
	v_bfe_u32 v115, v144, 5, 1
	v_lshl_add_u32 v114, v115, 10, v114
	v_lshrrev_b32_e32 v115, 6, v148
	v_lshl_add_u32 v114, v115, 15, v114
	s_mul_i32 vcc_lo, s47, 0x158000
	v_add_u32_e32 v114, vcc_lo, v114
	v_ashrrev_i32_e32 v115, 31, v114
	v_lshl_add_u64 v[126:127], v[152:153], 0, v[114:115]
	v_cvt_pk_bf16_f32 v116, v118, v119
	v_cvt_pk_bf16_f32 v118, v122, v123
	v_cvt_pk_bf16_f32 v119, v124, v125
	flat_store_dwordx4 v[126:127], v[116:119]
	s_andn2_b64 vcc, exec, s[12:13]
	s_mov_b64 s[12:13], -1
	v_add_f32_e32 v116, 1.0, v120
	v_add_f32_e32 v117, 1.0, v121
	v_rcp_f32_e32 v116, v116
	v_rcp_f32_e32 v117, v117
	v_or_b32_e32 v118, 16, v146
	v_mad_i64_i32 v[118:119], s[26:27], v118, s2, v[140:141]
	v_pk_mul_f32 v[110:111], v[110:111], v[116:117]
	v_mul_f32_e32 v116, 0xbfb8aa3b, v112
	v_mul_f32_e32 v117, 0xbfb8aa3b, v113
	v_exp_f32_e32 v116, v116
	v_exp_f32_e32 v117, v117
	v_pk_mul_f32 v[102:103], v[110:111], v[102:103]
	v_add_f32_e32 v110, 1.0, v116
	v_add_f32_e32 v111, 1.0, v117
	v_mul_f32_e32 v116, 0xbfb8aa3b, v106
	v_mul_f32_e32 v117, 0xbfb8aa3b, v107
	v_rcp_f32_e32 v110, v110
	v_rcp_f32_e32 v111, v111
	v_exp_f32_e32 v116, v116
	v_exp_f32_e32 v117, v117
	v_pk_mul_f32 v[110:111], v[112:113], v[110:111]
	v_add_f32_e32 v112, 1.0, v116
	v_add_f32_e32 v113, 1.0, v117
	v_mul_f32_e32 v116, 0xbfb8aa3b, v108
	v_mul_f32_e32 v117, 0xbfb8aa3b, v109
	v_exp_f32_e32 v116, v116
	v_exp_f32_e32 v117, v117
	v_rcp_f32_e32 v112, v112
	v_rcp_f32_e32 v113, v113
	v_add_f32_e32 v116, 1.0, v116
	v_add_f32_e32 v117, 1.0, v117
	v_rcp_f32_e32 v116, v116
	v_rcp_f32_e32 v117, v117
	v_pk_mul_f32 v[106:107], v[106:107], v[112:113]
	v_pk_mul_f32 v[104:105], v[110:111], v[104:105]
	v_pk_mul_f32 v[106:107], v[106:107], v[98:99]
	v_pk_mul_f32 v[98:99], v[108:109], v[116:117]
	v_lshl_add_u64 v[110:111], v[118:119], 0, v[114:115]
	v_pk_mul_f32 v[108:109], v[98:99], v[100:101]
	v_cvt_pk_bf16_f32 v98, v102, v103
	v_mul_f32_e32 v102, 0xbfb8aa3b, v94
	v_mul_f32_e32 v103, 0xbfb8aa3b, v95
	v_exp_f32_e32 v102, v102
	v_exp_f32_e32 v103, v103
	v_cvt_pk_bf16_f32 v99, v104, v105
	v_cvt_pk_bf16_f32 v100, v106, v107
	v_cvt_pk_bf16_f32 v101, v108, v109
	flat_store_dwordx4 v[110:111], v[98:101]
	s_nop 1
	v_add_f32_e32 v98, 1.0, v102
	v_add_f32_e32 v99, 1.0, v103
	v_rcp_f32_e32 v98, v98
	v_rcp_f32_e32 v99, v99
	v_or_b32_e32 v100, 32, v146
	v_mad_i64_i32 v[100:101], s[26:27], v100, s2, v[140:141]
	v_pk_mul_f32 v[94:95], v[94:95], v[98:99]
	v_mul_f32_e32 v98, 0xbfb8aa3b, v96
	v_mul_f32_e32 v99, 0xbfb8aa3b, v97
	v_exp_f32_e32 v98, v98
	v_exp_f32_e32 v99, v99
	v_pk_mul_f32 v[86:87], v[94:95], v[86:87]
	v_add_f32_e32 v94, 1.0, v98
	v_add_f32_e32 v95, 1.0, v99
	v_mul_f32_e32 v98, 0xbfb8aa3b, v90
	v_mul_f32_e32 v99, 0xbfb8aa3b, v91
	v_rcp_f32_e32 v94, v94
	v_rcp_f32_e32 v95, v95
	v_exp_f32_e32 v98, v98
	v_exp_f32_e32 v99, v99
	v_pk_mul_f32 v[94:95], v[96:97], v[94:95]
	v_add_f32_e32 v96, 1.0, v98
	v_add_f32_e32 v97, 1.0, v99
	v_mul_f32_e32 v98, 0xbfb8aa3b, v92
	v_mul_f32_e32 v99, 0xbfb8aa3b, v93
	v_exp_f32_e32 v98, v98
	v_exp_f32_e32 v99, v99
	v_rcp_f32_e32 v96, v96
	v_rcp_f32_e32 v97, v97
	v_add_f32_e32 v98, 1.0, v98
	v_add_f32_e32 v99, 1.0, v99
	v_rcp_f32_e32 v98, v98
	v_rcp_f32_e32 v99, v99
	v_pk_mul_f32 v[90:91], v[90:91], v[96:97]
	v_pk_mul_f32 v[88:89], v[94:95], v[88:89]
	v_pk_mul_f32 v[90:91], v[90:91], v[82:83]
	v_pk_mul_f32 v[82:83], v[92:93], v[98:99]
	v_lshl_add_u64 v[94:95], v[100:101], 0, v[114:115]
	v_pk_mul_f32 v[92:93], v[82:83], v[84:85]
	v_cvt_pk_bf16_f32 v82, v86, v87
	v_mul_f32_e32 v86, 0xbfb8aa3b, v78
	v_mul_f32_e32 v87, 0xbfb8aa3b, v79
	v_exp_f32_e32 v86, v86
	v_exp_f32_e32 v87, v87
; __device__ __forceinline__ unsigned cvtpk(float lo, float hi) { f32x2 v = {lo, hi}; bf16x2_t b = __builtin_convertvector(v, bf16x2_t); return __builtin_bit_cast(unsigned, b); }
; __device__ __forceinline__ float silu_f(float g) { return g * __builtin_amdgcn_rcpf(1.0f + fast_exp2(-g * LOG2E)); }
;     __device__ __forceinline__ void operator()(const f32x4 (&acc)[2][2][4][2], const Unit& u, int wr, int wc, int fr, int fq) const {
;     ...
;             for (int m = 0; m < 4; ++m) { bf16_t* rowp = O + (size_t)(row0 + ai * HALF + m * 16) * DFF + col0;
;                 float r[8];
; #pragma unroll
;                 for (int n = 0; n < 2; ++n)
; #pragma unroll
;                     for (int e = 0; e < 4; ++e) r[n * 4 + e] = silu_f(acc[ai][0][m][n][e]) * acc[ai][1][m][n][e];
;                 u32x4 w; w.x = cvtpk(r[0], r[1]); w.y = cvtpk(r[2], r[3]); w.z = cvtpk(r[4], r[5]); w.w = cvtpk(r[6], r[7]);
;                 *(u32x4*)rowp = w; }
	v_cvt_pk_bf16_f32 v83, v88, v89
	v_cvt_pk_bf16_f32 v84, v90, v91
	v_cvt_pk_bf16_f32 v85, v92, v93
	flat_store_dwordx4 v[94:95], v[82:85]
	s_nop 1
	v_add_f32_e32 v82, 1.0, v86
	v_add_f32_e32 v83, 1.0, v87
	v_rcp_f32_e32 v82, v82
	v_rcp_f32_e32 v83, v83
	v_or_b32_e32 v84, 48, v146
	v_mad_i64_i32 v[84:85], s[26:27], v84, s2, v[140:141]
	v_pk_mul_f32 v[78:79], v[78:79], v[82:83]
	v_mul_f32_e32 v82, 0xbfb8aa3b, v80
	v_mul_f32_e32 v83, 0xbfb8aa3b, v81
	v_exp_f32_e32 v82, v82
	v_exp_f32_e32 v83, v83
	v_pk_mul_f32 v[70:71], v[78:79], v[70:71]
	v_add_f32_e32 v78, 1.0, v82
	v_add_f32_e32 v79, 1.0, v83
	v_mul_f32_e32 v82, 0xbfb8aa3b, v74
	v_mul_f32_e32 v83, 0xbfb8aa3b, v75
	v_rcp_f32_e32 v78, v78
	v_rcp_f32_e32 v79, v79
	v_exp_f32_e32 v82, v82
	v_exp_f32_e32 v83, v83
	v_pk_mul_f32 v[78:79], v[80:81], v[78:79]
	v_add_f32_e32 v80, 1.0, v82
	v_add_f32_e32 v81, 1.0, v83
	v_mul_f32_e32 v82, 0xbfb8aa3b, v76
	v_mul_f32_e32 v83, 0xbfb8aa3b, v77
	v_exp_f32_e32 v82, v82
	v_exp_f32_e32 v83, v83
	v_rcp_f32_e32 v80, v80
	v_rcp_f32_e32 v81, v81
	v_add_f32_e32 v82, 1.0, v82
	v_add_f32_e32 v83, 1.0, v83
	v_rcp_f32_e32 v82, v82
	v_rcp_f32_e32 v83, v83
	v_pk_mul_f32 v[74:75], v[74:75], v[80:81]
	v_pk_mul_f32 v[72:73], v[78:79], v[72:73]
	v_pk_mul_f32 v[74:75], v[74:75], v[66:67]
	v_pk_mul_f32 v[66:67], v[76:77], v[82:83]
	v_lshl_add_u64 v[78:79], v[84:85], 0, v[114:115]
	v_pk_mul_f32 v[76:77], v[66:67], v[68:69]
	v_cvt_pk_bf16_f32 v66, v70, v71
	v_mul_f32_e32 v70, 0xbfb8aa3b, v62
	v_mul_f32_e32 v71, 0xbfb8aa3b, v63
	v_exp_f32_e32 v70, v70
	v_exp_f32_e32 v71, v71
	v_cvt_pk_bf16_f32 v67, v72, v73
	v_cvt_pk_bf16_f32 v68, v74, v75
	v_cvt_pk_bf16_f32 v69, v76, v77
	flat_store_dwordx4 v[78:79], v[66:69]
	s_nop 1
	v_add_f32_e32 v66, 1.0, v70
	v_add_f32_e32 v67, 1.0, v71
	v_rcp_f32_e32 v66, v66
	v_rcp_f32_e32 v67, v67
	v_add_u32_e32 v68, 0x80, v146
	v_mad_i64_i32 v[68:69], s[26:27], v68, s2, v[140:141]
	v_pk_mul_f32 v[62:63], v[62:63], v[66:67]
	v_mul_f32_e32 v66, 0xbfb8aa3b, v64
	v_mul_f32_e32 v67, 0xbfb8aa3b, v65
	v_exp_f32_e32 v66, v66
	v_exp_f32_e32 v67, v67
	v_pk_mul_f32 v[54:55], v[62:63], v[54:55]
	v_add_f32_e32 v62, 1.0, v66
	v_add_f32_e32 v63, 1.0, v67
	v_mul_f32_e32 v66, 0xbfb8aa3b, v58
	v_mul_f32_e32 v67, 0xbfb8aa3b, v59
	v_rcp_f32_e32 v62, v62
	v_rcp_f32_e32 v63, v63
	v_exp_f32_e32 v66, v66
	v_exp_f32_e32 v67, v67
	v_pk_mul_f32 v[62:63], v[64:65], v[62:63]
	v_add_f32_e32 v64, 1.0, v66
	v_add_f32_e32 v65, 1.0, v67
	v_mul_f32_e32 v66, 0xbfb8aa3b, v60
	v_mul_f32_e32 v67, 0xbfb8aa3b, v61
	v_exp_f32_e32 v66, v66
	v_exp_f32_e32 v67, v67
	v_rcp_f32_e32 v64, v64
	v_rcp_f32_e32 v65, v65
	v_add_f32_e32 v66, 1.0, v66
	v_add_f32_e32 v67, 1.0, v67
	v_rcp_f32_e32 v66, v66
	v_rcp_f32_e32 v67, v67
	v_pk_mul_f32 v[58:59], v[58:59], v[64:65]
	v_pk_mul_f32 v[56:57], v[62:63], v[56:57]
	v_pk_mul_f32 v[58:59], v[58:59], v[50:51]
	v_pk_mul_f32 v[50:51], v[60:61], v[66:67]
	v_lshl_add_u64 v[62:63], v[68:69], 0, v[114:115]
	v_pk_mul_f32 v[60:61], v[50:51], v[52:53]
	v_cvt_pk_bf16_f32 v50, v54, v55
	v_mul_f32_e32 v54, 0xbfb8aa3b, v46
	v_mul_f32_e32 v55, 0xbfb8aa3b, v47
	v_exp_f32_e32 v54, v54
	v_exp_f32_e32 v55, v55
	v_cvt_pk_bf16_f32 v51, v56, v57
	v_cvt_pk_bf16_f32 v52, v58, v59
	v_cvt_pk_bf16_f32 v53, v60, v61
	flat_store_dwordx4 v[62:63], v[50:53]
	s_nop 1
	v_add_f32_e32 v50, 1.0, v54
	v_add_f32_e32 v51, 1.0, v55
	v_rcp_f32_e32 v50, v50
	v_rcp_f32_e32 v51, v51
	v_add_u32_e32 v52, 0x90, v146
	v_mad_i64_i32 v[52:53], s[26:27], v52, s2, v[140:141]
	v_pk_mul_f32 v[46:47], v[46:47], v[50:51]
	v_mul_f32_e32 v50, 0xbfb8aa3b, v48
	v_mul_f32_e32 v51, 0xbfb8aa3b, v49
	v_exp_f32_e32 v50, v50
	v_exp_f32_e32 v51, v51
	v_pk_mul_f32 v[38:39], v[46:47], v[38:39]
	v_add_f32_e32 v46, 1.0, v50
	v_add_f32_e32 v47, 1.0, v51
	v_mul_f32_e32 v50, 0xbfb8aa3b, v42
	v_mul_f32_e32 v51, 0xbfb8aa3b, v43
	v_rcp_f32_e32 v46, v46
	v_rcp_f32_e32 v47, v47
	v_exp_f32_e32 v50, v50
	v_exp_f32_e32 v51, v51
	v_pk_mul_f32 v[46:47], v[48:49], v[46:47]
	v_add_f32_e32 v48, 1.0, v50
; __device__ __forceinline__ unsigned cvtpk(float lo, float hi) { f32x2 v = {lo, hi}; bf16x2_t b = __builtin_convertvector(v, bf16x2_t); return __builtin_bit_cast(unsigned, b); }
; __device__ __forceinline__ float silu_f(float g) { return g * __builtin_amdgcn_rcpf(1.0f + fast_exp2(-g * LOG2E)); }
;     __device__ __forceinline__ void operator()(const f32x4 (&acc)[2][2][4][2], const Unit& u, int wr, int wc, int fr, int fq) const {
;     ...
;         for (int ai = 0; ai < 2; ++ai)
; #pragma unroll
;             for (int m = 0; m < 4; ++m) { bf16_t* rowp = O + (size_t)(row0 + ai * HALF + m * 16) * DFF + col0;
;                 float r[8];
; #pragma unroll
;                 for (int n = 0; n < 2; ++n)
; #pragma unroll
;                     for (int e = 0; e < 4; ++e) r[n * 4 + e] = silu_f(acc[ai][0][m][n][e]) * acc[ai][1][m][n][e];
;                 u32x4 w; w.x = cvtpk(r[0], r[1]); w.y = cvtpk(r[2], r[3]); w.z = cvtpk(r[4], r[5]); w.w = cvtpk(r[6], r[7]);
;                 *(u32x4*)rowp = w; }
	v_add_f32_e32 v49, 1.0, v51
	v_mul_f32_e32 v50, 0xbfb8aa3b, v44
	v_mul_f32_e32 v51, 0xbfb8aa3b, v45
	v_exp_f32_e32 v50, v50
	v_exp_f32_e32 v51, v51
	v_rcp_f32_e32 v48, v48
	v_rcp_f32_e32 v49, v49
	v_add_f32_e32 v50, 1.0, v50
	v_add_f32_e32 v51, 1.0, v51
	v_rcp_f32_e32 v50, v50
	v_rcp_f32_e32 v51, v51
	v_pk_mul_f32 v[42:43], v[42:43], v[48:49]
	v_pk_mul_f32 v[40:41], v[46:47], v[40:41]
	v_pk_mul_f32 v[42:43], v[42:43], v[34:35]
	v_pk_mul_f32 v[34:35], v[44:45], v[50:51]
	v_lshl_add_u64 v[46:47], v[52:53], 0, v[114:115]
	v_pk_mul_f32 v[44:45], v[34:35], v[36:37]
	v_cvt_pk_bf16_f32 v34, v38, v39
	v_mul_f32_e32 v38, 0xbfb8aa3b, v30
	v_mul_f32_e32 v39, 0xbfb8aa3b, v31
	v_exp_f32_e32 v38, v38
	v_exp_f32_e32 v39, v39
	v_cvt_pk_bf16_f32 v35, v40, v41
	v_cvt_pk_bf16_f32 v36, v42, v43
	v_cvt_pk_bf16_f32 v37, v44, v45
	flat_store_dwordx4 v[46:47], v[34:37]
	s_nop 1
	v_add_f32_e32 v34, 1.0, v38
	v_add_f32_e32 v35, 1.0, v39
	v_rcp_f32_e32 v34, v34
	v_rcp_f32_e32 v35, v35
	v_add_u32_e32 v36, 0xa0, v146
	v_mad_i64_i32 v[36:37], s[26:27], v36, s2, v[140:141]
	v_pk_mul_f32 v[30:31], v[30:31], v[34:35]
	v_mul_f32_e32 v34, 0xbfb8aa3b, v32
	v_mul_f32_e32 v35, 0xbfb8aa3b, v33
	v_exp_f32_e32 v34, v34
	v_exp_f32_e32 v35, v35
	v_pk_mul_f32 v[22:23], v[30:31], v[22:23]
	v_add_f32_e32 v30, 1.0, v34
	v_add_f32_e32 v31, 1.0, v35
	v_mul_f32_e32 v34, 0xbfb8aa3b, v26
	v_mul_f32_e32 v35, 0xbfb8aa3b, v27
	v_rcp_f32_e32 v30, v30
	v_rcp_f32_e32 v31, v31
	v_exp_f32_e32 v34, v34
	v_exp_f32_e32 v35, v35
	v_pk_mul_f32 v[30:31], v[32:33], v[30:31]
	v_add_f32_e32 v32, 1.0, v34
	v_add_f32_e32 v33, 1.0, v35
	v_mul_f32_e32 v34, 0xbfb8aa3b, v28
	v_mul_f32_e32 v35, 0xbfb8aa3b, v29
	v_exp_f32_e32 v34, v34
	v_exp_f32_e32 v35, v35
	v_rcp_f32_e32 v32, v32
	v_rcp_f32_e32 v33, v33
	v_add_f32_e32 v34, 1.0, v34
	v_add_f32_e32 v35, 1.0, v35
	v_rcp_f32_e32 v34, v34
	v_rcp_f32_e32 v35, v35
	v_pk_mul_f32 v[26:27], v[26:27], v[32:33]
	v_pk_mul_f32 v[24:25], v[30:31], v[24:25]
	v_pk_mul_f32 v[26:27], v[26:27], v[18:19]
	v_pk_mul_f32 v[18:19], v[28:29], v[34:35]
	v_lshl_add_u64 v[30:31], v[36:37], 0, v[114:115]
	v_pk_mul_f32 v[28:29], v[18:19], v[20:21]
	v_cvt_pk_bf16_f32 v18, v22, v23
	v_mul_f32_e32 v22, 0xbfb8aa3b, v12
	v_mul_f32_e32 v23, 0xbfb8aa3b, v13
	v_exp_f32_e32 v22, v22
	v_exp_f32_e32 v23, v23
	v_cvt_pk_bf16_f32 v19, v24, v25
	v_cvt_pk_bf16_f32 v20, v26, v27
	v_cvt_pk_bf16_f32 v21, v28, v29
	flat_store_dwordx4 v[30:31], v[18:21]
	s_nop 1
	v_add_f32_e32 v18, 1.0, v22
	v_add_f32_e32 v19, 1.0, v23
	v_rcp_f32_e32 v18, v18
	v_rcp_f32_e32 v19, v19
	v_add_u32_e32 v20, 0xb0, v146
	v_mad_i64_i32 v[20:21], s[26:27], v20, s2, v[140:141]
	v_pk_mul_f32 v[12:13], v[12:13], v[18:19]
	v_mul_f32_e32 v18, 0xbfb8aa3b, v14
	v_mul_f32_e32 v19, 0xbfb8aa3b, v15
	v_exp_f32_e32 v18, v18
	v_exp_f32_e32 v19, v19
	v_pk_mul_f32 v[4:5], v[12:13], v[4:5]
	v_add_f32_e32 v12, 1.0, v18
	v_add_f32_e32 v13, 1.0, v19
	v_mul_f32_e32 v18, 0xbfb8aa3b, v8
	v_mul_f32_e32 v19, 0xbfb8aa3b, v9
	v_rcp_f32_e32 v12, v12
	v_rcp_f32_e32 v13, v13
	v_exp_f32_e32 v18, v18
	v_exp_f32_e32 v19, v19
	v_pk_mul_f32 v[12:13], v[14:15], v[12:13]
	v_add_f32_e32 v14, 1.0, v18
	v_add_f32_e32 v15, 1.0, v19
	v_mul_f32_e32 v18, 0xbfb8aa3b, v10
	v_mul_f32_e32 v19, 0xbfb8aa3b, v11
	v_exp_f32_e32 v18, v18
	v_exp_f32_e32 v19, v19
	v_rcp_f32_e32 v14, v14
	v_rcp_f32_e32 v15, v15
	v_add_f32_e32 v18, 1.0, v18
	v_add_f32_e32 v19, 1.0, v19
	v_rcp_f32_e32 v18, v18
	v_rcp_f32_e32 v19, v19
	v_pk_mul_f32 v[8:9], v[8:9], v[14:15]
	v_pk_mul_f32 v[6:7], v[12:13], v[6:7]
	v_pk_mul_f32 v[8:9], v[8:9], v[0:1]
	v_pk_mul_f32 v[0:1], v[10:11], v[18:19]
	v_lshl_add_u64 v[12:13], v[20:21], 0, v[114:115]
	v_pk_mul_f32 v[10:11], v[0:1], v[2:3]
	v_cvt_pk_bf16_f32 v0, v4, v5
	v_cvt_pk_bf16_f32 v1, v6, v7
	v_cvt_pk_bf16_f32 v2, v8, v9
	v_cvt_pk_bf16_f32 v3, v10, v11
	flat_store_dwordx4 v[12:13], v[0:3]
	s_cbranch_vccnz .LBB0_697
	s_andn2_b64 vcc, exec, s[0:1]
	s_cbranch_vccnz .LBB0_696
	s_barrier
	s_branch .LBB0_696

; __global__ void __launch_bounds__(NTHREADS, 2) fwd_megakernel(Params p) {
	.amdhsa_kernel _Z14fwd_megakernel6Params
		.amdhsa_group_segment_fixed_size 0
		.amdhsa_private_segment_fixed_size 0
		.amdhsa_kernarg_size 472
		.amdhsa_user_sgpr_count 2
		.amdhsa_user_sgpr_dispatch_ptr 0
		.amdhsa_user_sgpr_queue_ptr 0
		.amdhsa_user_sgpr_kernarg_segment_ptr 1
		.amdhsa_user_sgpr_dispatch_id 0
		.amdhsa_user_sgpr_kernarg_preload_length 0
		.amdhsa_user_sgpr_kernarg_preload_offset 0
		.amdhsa_user_sgpr_private_segment_size 0
		.amdhsa_uses_dynamic_stack 0
		.amdhsa_enable_private_segment 0
		.amdhsa_system_sgpr_workgroup_id_x 1
		.amdhsa_system_sgpr_workgroup_id_y 0
		.amdhsa_system_sgpr_workgroup_id_z 0
		.amdhsa_system_sgpr_workgroup_info 0
		.amdhsa_system_vgpr_workitem_id 2
		.amdhsa_next_free_vgpr 256
		.amdhsa_next_free_sgpr 102
		.amdhsa_accum_offset 256
		.amdhsa_reserve_vcc 1
		.amdhsa_float_round_mode_32 0
		.amdhsa_float_round_mode_16_64 0
		.amdhsa_float_denorm_mode_32 3
		.amdhsa_float_denorm_mode_16_64 3
		.amdhsa_dx10_clamp 1
		.amdhsa_ieee_mode 1
		.amdhsa_fp16_overflow 0
		.amdhsa_tg_split 0
		.amdhsa_exception_fp_ieee_invalid_op 0
		.amdhsa_exception_fp_denorm_src 0
		.amdhsa_exception_fp_ieee_div_zero 0
		.amdhsa_exception_fp_ieee_overflow 0
		.amdhsa_exception_fp_ieee_underflow 0
		.amdhsa_exception_fp_ieee_inexact 0
		.amdhsa_exception_int_div_zero 0
	.end_amdhsa_kernel

; __global__ void __launch_bounds__(NTHREADS, 2) fwd_megakernel(Params p) {
amdhsa.kernels:
  - .agpr_count:     0
    .args:
      - .offset:         0
        .size:           216
        .value_kind:     by_value
      - .offset:         216
        .size:           4
        .value_kind:     hidden_block_count_x
      - .offset:         220
        .size:           4
        .value_kind:     hidden_block_count_y
      - .offset:         224
        .size:           4
        .value_kind:     hidden_block_count_z
      - .offset:         228
        .size:           2
        .value_kind:     hidden_group_size_x
      - .offset:         230
        .size:           2
        .value_kind:     hidden_group_size_y
      - .offset:         232
        .size:           2
        .value_kind:     hidden_group_size_z
      - .offset:         234
        .size:           2
        .value_kind:     hidden_remainder_x
      - .offset:         236
        .size:           2
        .value_kind:     hidden_remainder_y
      - .offset:         238
        .size:           2
        .value_kind:     hidden_remainder_z
      - .offset:         256
        .size:           8
        .value_kind:     hidden_global_offset_x
      - .offset:         264
        .size:           8
        .value_kind:     hidden_global_offset_y
      - .offset:         272
        .size:           8
        .value_kind:     hidden_global_offset_z
      - .offset:         280
        .size:           2
        .value_kind:     hidden_grid_dims
      - .offset:         304
        .size:           8
        .value_kind:     hidden_multigrid_sync_arg
      - .offset:         336
        .size:           4
        .value_kind:     hidden_dynamic_lds_size
    .group_segment_fixed_size: 0
    .kernarg_segment_align: 8
    .kernarg_segment_size: 472
    .language:       OpenCL C
    .language_version:
      - 2
      - 0
    .max_flat_workgroup_size: 512
    .name:           _Z14fwd_megakernel6Params
    .private_segment_fixed_size: 0
    .sgpr_count:     108
    .sgpr_spill_count: 420
    .symbol:         _Z14fwd_megakernel6Params.kd
    .uniform_work_group_size: 1
    .uses_dynamic_stack: false
    .vgpr_count:     256
    .vgpr_spill_count: 0
    .wavefront_size: 64
